# out-norm phase: the four 16-byte row loads issued together (one memory round trip per row instead of two)
# baseline (speedup 1.0000x reference)
; __device__ __forceinline__ unsigned cvt_pk_bf16(float lo, float hi) { unsigned r; asm volatile("v_cvt_pk_bf16_f32 %0, %1, %2" : "=v"(r) : "v"(lo), "v"(hi)); return r; }
; __device__ __forceinline__ float bf_lo(unsigned w) { return __uint_as_float(w << 16); }
; __device__ __forceinline__ float bf_hi(unsigned w) { return __uint_as_float(w & 0xffff0000u); }
; __global__ void __launch_bounds__(NWAVES * 64, 2) mk_fwd(Args a) {
;     ...
;             for (int m = gw; m < T; m += NGW) { u32x4* hr = (u32x4*)(H + (size_t)m * DM) + lane; u32x4 w[4]; float s1 = 0.f, s2 = 0.f;
; #pragma unroll
;                 for (int j = 0; j < 4; ++j) { w[j] = hr[64 * j]; float s = 0.f;
; #pragma unroll
;                     for (int i = 0; i < 4; ++i) { const float lo = bf_lo(w[j][i]), hi = bf_hi(w[j][i]); s += lo * lo + hi * hi; }
;                     if (j < 2) s1 += s; else s2 += s; }
;                 s1 = wave_sum(s1, lane); s2 = wave_sum(s2, lane);
;                 const float r1 = rsqrtf(s1 * (1.f / 1024) + EPS), r2 = rsqrtf(s2 * (1.f / 1024) + EPS);
; #pragma unroll
;                 for (int j = 0; j < 4; ++j) { const float rr = j < 2 ? r1 : r2; u32x4 o;
; #pragma unroll
;                     for (int i = 0; i < 4; ++i) { const float g0 = (i < 2) ? gv[j][0][2 * i] : gv[j][1][2 * i - 4], g1 = (i < 2) ? gv[j][0][2 * i + 1] : gv[j][1][2 * i - 3];
;                         o[i] = cvt_pk_bf16(bf_lo(w[j][i]) * rr * g0, bf_hi(w[j][i]) * rr * g1); }
;                     hr[64 * j] = o; } }
.LBB0_452:
	flat_load_dwordx4 v[32:35], v[36:37]
	flat_load_dwordx4 v[54:57], v[36:37] offset:1024
	flat_load_dwordx4 v[80:83], v[36:37] offset:2048
	flat_load_dwordx4 v[64:67], v[36:37] offset:3072
	s_mov_b32 s0, 0x3a800000
	s_add_i32 s6, s6, s28
	s_cmpk_gt_i32 s6, 0x7fff
	s_waitcnt vmcnt(0) lgkmcnt(0)
	v_and_b32_e32 v50, 0xffff0000, v32
	v_and_b32_e32 v51, 0xffff0000, v54
	v_and_b32_e32 v47, 0xffff0000, v55
	v_and_b32_e32 v46, 0xffff0000, v33
	v_lshlrev_b32_e32 v53, 16, v54
	v_lshlrev_b32_e32 v52, 16, v32
	v_pk_mul_f32 v[38:39], v[50:51], v[50:51]
	v_lshlrev_b32_e32 v49, 16, v55
	v_lshlrev_b32_e32 v48, 16, v33
	v_pk_mul_f32 v[32:33], v[46:47], v[46:47]
	v_pk_fma_f32 v[38:39], v[52:53], v[52:53], v[38:39]
	v_pk_fma_f32 v[32:33], v[48:49], v[48:49], v[32:33]
	v_and_b32_e32 v43, 0xffff0000, v56
	v_and_b32_e32 v42, 0xffff0000, v34
	v_pk_add_f32 v[32:33], v[38:39], v[32:33]
	v_lshlrev_b32_e32 v45, 16, v56
	v_lshlrev_b32_e32 v44, 16, v34
	v_pk_mul_f32 v[38:39], v[42:43], v[42:43]
	v_lshlrev_b32_e32 v40, 16, v35
	v_pk_fma_f32 v[38:39], v[44:45], v[44:45], v[38:39]
	v_lshlrev_b32_e32 v41, 16, v57
	v_pk_add_f32 v[32:33], v[32:33], v[38:39]
	v_and_b32_e32 v39, 0xffff0000, v57
	v_and_b32_e32 v38, 0xffff0000, v35
	v_pk_mul_f32 v[34:35], v[38:39], v[38:39]
	s_nop 0
	v_pk_fma_f32 v[34:35], v[40:41], v[40:41], v[34:35]
	s_nop 0
	v_pk_add_f32 v[68:69], v[32:33], v[34:35]
	v_mov_b32_e32 v32, v80
	v_mov_b32_e32 v33, v81
	v_mov_b32_e32 v34, v82
	v_mov_b32_e32 v35, v83
	v_and_b32_e32 v56, 0xffff0000, v32
	v_and_b32_e32 v57, 0xffff0000, v64
	v_lshlrev_b32_e32 v55, 16, v64
	v_lshlrev_b32_e32 v54, 16, v32
	v_pk_mul_f32 v[58:59], v[56:57], v[56:57]
	v_and_b32_e32 v61, 0xffff0000, v65
	v_and_b32_e32 v60, 0xffff0000, v33
	v_pk_fma_f32 v[62:63], v[54:55], v[54:55], v[58:59]
	v_lshlrev_b32_e32 v59, 16, v65
	v_lshlrev_b32_e32 v58, 16, v33
	v_pk_mul_f32 v[32:33], v[60:61], v[60:61]
	s_nop 0
	v_pk_fma_f32 v[32:33], v[58:59], v[58:59], v[32:33]
	s_nop 0
	v_pk_add_f32 v[64:65], v[62:63], v[32:33]
	v_and_b32_e32 v63, 0xffff0000, v66
	v_and_b32_e32 v62, 0xffff0000, v34
	v_lshlrev_b32_e32 v33, 16, v66
	v_lshlrev_b32_e32 v32, 16, v34
	v_pk_mul_f32 v[76:77], v[62:63], v[62:63]
	v_and_b32_e32 v66, 0xffff0000, v35
	v_pk_fma_f32 v[76:77], v[32:33], v[32:33], v[76:77]
	s_nop 0
	v_pk_add_f32 v[76:77], v[64:65], v[76:77]
	v_lshlrev_b32_e32 v65, 16, v67
	v_and_b32_e32 v67, 0xffff0000, v67
	v_lshlrev_b32_e32 v64, 16, v35
	v_pk_mul_f32 v[34:35], v[66:67], v[66:67]
	s_nop 0
	v_pk_fma_f32 v[34:35], v[64:65], v[64:65], v[34:35]
	s_nop 0
	v_pk_add_f32 v[34:35], v[76:77], v[34:35]
	v_mov_b32_e32 v77, v68
	v_mov_b32_e32 v76, v34
	v_mov_b32_e32 v68, v35
	v_pk_add_f32 v[34:35], v[76:77], v[68:69]
	ds_bpermute_b32 v69, v70, v35
	ds_bpermute_b32 v68, v70, v34
	s_waitcnt lgkmcnt(0)
	v_pk_add_f32 v[34:35], v[34:35], v[68:69]
	ds_bpermute_b32 v69, v71, v35
	ds_bpermute_b32 v68, v71, v34
	s_waitcnt lgkmcnt(0)
	v_pk_add_f32 v[34:35], v[34:35], v[68:69]
	ds_bpermute_b32 v69, v72, v35
	ds_bpermute_b32 v68, v72, v34
	s_waitcnt lgkmcnt(0)
	v_pk_add_f32 v[34:35], v[34:35], v[68:69]
	ds_bpermute_b32 v69, v73, v35
	ds_bpermute_b32 v68, v73, v34
	s_waitcnt lgkmcnt(0)
	v_pk_add_f32 v[34:35], v[34:35], v[68:69]
	ds_bpermute_b32 v69, v74, v35
	ds_bpermute_b32 v68, v74, v34
	s_waitcnt lgkmcnt(0)
	v_pk_add_f32 v[34:35], v[34:35], v[68:69]
	ds_bpermute_b32 v69, v75, v35
	ds_bpermute_b32 v68, v75, v34
	s_waitcnt lgkmcnt(0)
	v_pk_add_f32 v[34:35], v[34:35], v[68:69]
	s_nop 0
	v_pk_fma_f32 v[34:35], v[34:35], s[0:1], v[232:233] op_sel_hi:[1,0,0]
	s_nop 0
	v_mul_f32_e32 v68, 0x4b800000, v35
	v_cmp_gt_f32_e64 s[0:1], s4, v35
	v_cmp_gt_f32_e32 vcc, s4, v34
	s_nop 0
	v_cndmask_b32_e64 v35, v35, v68, s[0:1]
	v_rsq_f32_e32 v35, v35
	s_nop 0
	v_mul_f32_e32 v68, 0x45800000, v35
	v_cndmask_b32_e64 v35, v35, v68, s[0:1]
	v_mul_f32_e32 v38, v35, v38
	v_mul_f32_e32 v52, v35, v52
	v_mul_f32_e32 v50, v35, v50
	v_mul_f32_e32 v48, v35, v48
	v_mul_f32_e32 v46, v35, v46
	v_mul_f32_e32 v44, v35, v44
	v_mul_f32_e32 v42, v35, v42
	v_mul_f32_e32 v40, v35, v40
	v_mul_f32_e32 v38, v38, v7
	v_mul_f32_e32 v68, 0x4b800000, v34
	v_mul_f32_e32 v52, v52, v0
	v_mul_f32_e32 v50, v50, v1
	v_cvt_pk_bf16_f32 v76, v52, v50
	v_mul_f32_e32 v48, v48, v2
	v_mul_f32_e32 v46, v46, v3
	v_cvt_pk_bf16_f32 v77, v48, v46
	v_mul_f32_e32 v44, v44, v4
	v_mul_f32_e32 v42, v42, v5
	v_cvt_pk_bf16_f32 v78, v44, v42
	v_mul_f32_e32 v40, v40, v6
	v_cvt_pk_bf16_f32 v79, v40, v38
	v_mul_f32_e32 v38, v35, v53
	v_cndmask_b32_e32 v34, v34, v68, vcc
	v_mul_f32_e32 v38, v38, v8
	v_mul_f32_e32 v40, v35, v51
	v_rsq_f32_e32 v34, v34
	flat_store_dwordx4 v[36:37], v[76:79]
	v_mul_f32_e32 v40, v40, v9
	v_cvt_pk_bf16_f32 v46, v38, v40
	v_mul_f32_e32 v38, v35, v49
	v_mul_f32_e32 v38, v38, v10
	v_mul_f32_e32 v40, v35, v47
	v_mul_f32_e32 v40, v40, v11
	v_cvt_pk_bf16_f32 v47, v38, v40
	v_mul_f32_e32 v38, v35, v45
	v_mul_f32_e32 v38, v38, v12
	v_mul_f32_e32 v40, v35, v43
	v_mul_f32_e32 v68, 0x45800000, v34
	v_mul_f32_e32 v40, v40, v13
	v_cvt_pk_bf16_f32 v48, v38, v40
	v_mul_f32_e32 v38, v35, v41
	v_mul_f32_e32 v35, v35, v39
	v_cndmask_b32_e32 v34, v34, v68, vcc
	v_mul_f32_e32 v38, v38, v14
	v_mul_f32_e32 v35, v35, v15
	v_cvt_pk_bf16_f32 v49, v38, v35
	v_mul_f32_e32 v35, v34, v54
	v_mul_f32_e32 v38, v34, v56
	v_mul_f32_e32 v35, v35, v16
	v_mul_f32_e32 v38, v38, v17
	flat_store_dwordx4 v[36:37], v[46:49] offset:1024
	v_cvt_pk_bf16_f32 v38, v35, v38
	v_mul_f32_e32 v35, v34, v58
	v_mul_f32_e32 v39, v34, v60
	v_mul_f32_e32 v35, v35, v18
	v_mul_f32_e32 v39, v39, v19
	v_mul_f32_e32 v32, v34, v32
	v_cvt_pk_bf16_f32 v39, v35, v39
	v_mul_f32_e32 v32, v32, v20
	v_mul_f32_e32 v35, v34, v62
	v_mul_f32_e32 v35, v35, v21
	v_cvt_pk_bf16_f32 v40, v32, v35
	v_mul_f32_e32 v32, v34, v64
	v_mul_f32_e32 v32, v32, v22
	v_mul_f32_e32 v35, v34, v66
	v_mul_f32_e32 v35, v35, v23
	v_cvt_pk_bf16_f32 v41, v32, v35
	v_mul_f32_e32 v32, v34, v55
	v_mul_f32_e32 v32, v32, v24
	v_mul_f32_e32 v35, v34, v57
	flat_store_dwordx4 v[36:37], v[38:41] offset:2048
	v_mul_f32_e32 v35, v35, v25
	s_nop 0
	v_cvt_pk_bf16_f32 v38, v32, v35
	v_mul_f32_e32 v32, v34, v59
	v_mul_f32_e32 v32, v32, v26
	v_mul_f32_e32 v35, v34, v61
	v_mul_f32_e32 v35, v35, v27
	v_cvt_pk_bf16_f32 v39, v32, v35
	v_mul_f32_e32 v32, v34, v33
	v_mul_f32_e32 v33, v34, v63
	v_mul_f32_e32 v32, v32, v28
	v_mul_f32_e32 v33, v33, v29
	v_cvt_pk_bf16_f32 v40, v32, v33
	v_mul_f32_e32 v32, v34, v65
	v_mul_f32_e32 v33, v34, v67
	v_mul_f32_e32 v32, v32, v30
	v_mul_f32_e32 v33, v33, v31
	v_cvt_pk_bf16_f32 v41, v32, v33
	flat_store_dwordx4 v[36:37], v[38:41] offset:3072
	v_lshl_add_u64 v[36:37], v[36:37], 0, s[10:11]
	s_cbranch_scc0 .LBB0_452
